# E59: f32 output stores (K/V projections, final y, mem k/v): streaming hint removed (nt -> plain write-back); on E41
# speedup vs baseline: 1.0060x; 1.0060x over previous
.LBB0_220:
	v_lshl_add_u32 v148, s4, 8, v154
	s_lshl_b32 s4, s48, 8
	s_and_b32 s4, s4, 0x100
	s_cmp_eq_u32 s5, 1
	s_cselect_b64 vcc, -1, 0
	v_ashrrev_i32_e32 v149, 31, v148
	v_or_b32_e32 v161, s4, v156
	v_cndmask_b32_e32 v146, 1.0, v160, vcc
	v_lshlrev_b64 v[150:151], 9, v[148:149]
	v_cndmask_b32_e64 v146, v146, 1.0, s[84:85]
	s_cmp_lg_u64 s[78:79], 0
	v_or_b32_e32 v150, v150, v161
	s_cselect_b64 s[48:49], -1, 0
	s_cmp_eq_u64 s[78:79], 0
	v_lshl_add_u64 v[152:153], v[150:151], 1, s[76:77]
	v_lshl_add_u64 v[150:151], v[150:151], 2, s[78:79]
	v_pk_mul_f32 v[128:129], v[146:147], v[128:129] op_sel_hi:[0,1]
	v_pk_mul_f32 v[126:127], v[146:147], v[126:127] op_sel_hi:[0,1]
	v_pk_mul_f32 v[124:125], v[146:147], v[124:125] op_sel_hi:[0,1]
	v_pk_mul_f32 v[122:123], v[146:147], v[122:123] op_sel_hi:[0,1]
	v_cvt_pk_bf16_f32 v164, v126, v127
	v_cvt_pk_bf16_f32 v165, v128, v129
	v_cvt_pk_bf16_f32 v166, v122, v123
	v_cvt_pk_bf16_f32 v167, v124, v125
	global_store_dwordx4 v[152:153], v[164:167], off sc1
	s_cbranch_scc1 .LBB0_222
	global_store_dwordx4 v[150:151], v[126:129], off
	global_store_dwordx4 v[150:151], v[122:125], off offset:16
.LBB0_222:
	v_mov_b32_e32 v147, v146
	s_nop 0
	v_mov_b32_e32 v122, v146
	v_mov_b32_e32 v123, v146
	v_pk_mul_f32 v[118:119], v[146:147], v[118:119]
	v_pk_mul_f32 v[120:121], v[122:123], v[120:121]
	v_cvt_pk_bf16_f32 v124, v118, v119
	v_pk_mul_f32 v[116:117], v[122:123], v[116:117]
	v_pk_mul_f32 v[114:115], v[146:147], v[114:115]
	v_cvt_pk_bf16_f32 v125, v120, v121
	s_andn2_b64 vcc, exec, s[48:49]
	v_cvt_pk_bf16_f32 v126, v114, v115
	v_cvt_pk_bf16_f32 v127, v116, v117
	global_store_dwordx4 v[152:153], v[124:127], off offset:256 sc1
	s_nop 1
	v_cndmask_b32_e64 v124, 0, 1, s[48:49]
	v_cmp_ne_u32_e64 s[4:5], 1, v124
	s_cbranch_vccnz .LBB0_224
	global_store_dwordx4 v[150:151], v[118:121], off offset:512
	global_store_dwordx4 v[150:151], v[114:117], off offset:528
.LBB0_224:
	s_nop 1
	v_or_b32_e32 v114, 16, v148
	v_ashrrev_i32_e32 v115, 31, v114
	v_lshlrev_b64 v[114:115], 9, v[114:115]
	v_or_b32_e32 v114, v114, v161
	v_lshl_add_u64 v[116:117], v[114:115], 1, s[76:77]
	v_lshl_add_u64 v[114:115], v[114:115], 2, s[78:79]
	v_pk_mul_f32 v[112:113], v[122:123], v[112:113]
	v_pk_mul_f32 v[110:111], v[146:147], v[110:111]
	v_pk_mul_f32 v[108:109], v[122:123], v[108:109]
	v_pk_mul_f32 v[106:107], v[146:147], v[106:107]
	s_and_b64 vcc, exec, s[4:5]
	v_cvt_pk_bf16_f32 v118, v110, v111
	v_cvt_pk_bf16_f32 v119, v112, v113
	v_cvt_pk_bf16_f32 v120, v106, v107
	v_cvt_pk_bf16_f32 v121, v108, v109
	global_store_dwordx4 v[116:117], v[118:121], off sc1
	s_cbranch_vccnz .LBB0_226
	global_store_dwordx4 v[114:115], v[110:113], off
	global_store_dwordx4 v[114:115], v[106:109], off offset:16
.LBB0_226:
	s_nop 1
	v_mov_b32_e32 v106, v146
	v_mov_b32_e32 v107, v146
	v_pk_mul_f32 v[104:105], v[106:107], v[104:105]
	v_pk_mul_f32 v[102:103], v[146:147], v[102:103]
	v_pk_mul_f32 v[100:101], v[106:107], v[100:101]
	v_pk_mul_f32 v[98:99], v[146:147], v[98:99]
	s_and_b64 vcc, exec, s[4:5]
	v_cvt_pk_bf16_f32 v108, v102, v103
	v_cvt_pk_bf16_f32 v109, v104, v105
	v_cvt_pk_bf16_f32 v110, v98, v99
	v_cvt_pk_bf16_f32 v111, v100, v101
	global_store_dwordx4 v[116:117], v[108:111], off offset:256 sc1
	s_cbranch_vccnz .LBB0_228
	global_store_dwordx4 v[114:115], v[102:105], off offset:512
	global_store_dwordx4 v[114:115], v[98:101], off offset:528
.LBB0_228:
	s_nop 1
	v_or_b32_e32 v98, 32, v148
	v_ashrrev_i32_e32 v99, 31, v98
	v_lshlrev_b64 v[98:99], 9, v[98:99]
	v_or_b32_e32 v98, v98, v161
	v_lshl_add_u64 v[100:101], v[98:99], 1, s[76:77]
	v_lshl_add_u64 v[98:99], v[98:99], 2, s[78:79]
	v_pk_mul_f32 v[96:97], v[106:107], v[96:97]
	v_pk_mul_f32 v[94:95], v[146:147], v[94:95]
	v_pk_mul_f32 v[92:93], v[106:107], v[92:93]
	v_pk_mul_f32 v[90:91], v[146:147], v[90:91]
	s_and_b64 vcc, exec, s[4:5]
	v_cvt_pk_bf16_f32 v102, v94, v95
	v_cvt_pk_bf16_f32 v103, v96, v97
	v_cvt_pk_bf16_f32 v104, v90, v91
	v_cvt_pk_bf16_f32 v105, v92, v93
	global_store_dwordx4 v[100:101], v[102:105], off sc1
	s_cbranch_vccnz .LBB0_230
	global_store_dwordx4 v[98:99], v[94:97], off
	global_store_dwordx4 v[98:99], v[90:93], off offset:16
.LBB0_230:
	s_nop 1
	v_mov_b32_e32 v90, v146
	v_mov_b32_e32 v91, v146
	v_pk_mul_f32 v[88:89], v[90:91], v[88:89]
	v_pk_mul_f32 v[86:87], v[146:147], v[86:87]
	v_pk_mul_f32 v[84:85], v[90:91], v[84:85]
	v_pk_mul_f32 v[82:83], v[146:147], v[82:83]
	s_and_b64 vcc, exec, s[4:5]
	v_cvt_pk_bf16_f32 v92, v86, v87
	v_cvt_pk_bf16_f32 v93, v88, v89
	v_cvt_pk_bf16_f32 v94, v82, v83
	v_cvt_pk_bf16_f32 v95, v84, v85
	global_store_dwordx4 v[100:101], v[92:95], off offset:256 sc1
	s_cbranch_vccnz .LBB0_232
	global_store_dwordx4 v[98:99], v[86:89], off offset:512
	global_store_dwordx4 v[98:99], v[82:85], off offset:528
.LBB0_232:
	s_nop 1
	v_or_b32_e32 v82, 48, v148
	v_ashrrev_i32_e32 v83, 31, v82
	v_lshlrev_b64 v[82:83], 9, v[82:83]
	v_or_b32_e32 v82, v82, v161
	v_lshl_add_u64 v[84:85], v[82:83], 1, s[76:77]
	v_lshl_add_u64 v[82:83], v[82:83], 2, s[78:79]
	v_pk_mul_f32 v[80:81], v[90:91], v[80:81]
	v_pk_mul_f32 v[78:79], v[146:147], v[78:79]
	v_pk_mul_f32 v[76:77], v[90:91], v[76:77]
	v_pk_mul_f32 v[74:75], v[146:147], v[74:75]
	s_and_b64 vcc, exec, s[4:5]
	v_cvt_pk_bf16_f32 v86, v78, v79
	v_cvt_pk_bf16_f32 v87, v80, v81
	v_cvt_pk_bf16_f32 v88, v74, v75
	v_cvt_pk_bf16_f32 v89, v76, v77
	global_store_dwordx4 v[84:85], v[86:89], off sc1
	s_cbranch_vccnz .LBB0_234
	global_store_dwordx4 v[82:83], v[78:81], off
	global_store_dwordx4 v[82:83], v[74:77], off offset:16
.LBB0_234:
	s_nop 1
	v_mov_b32_e32 v74, v146
	v_mov_b32_e32 v75, v146
	v_pk_mul_f32 v[72:73], v[74:75], v[72:73]
	v_pk_mul_f32 v[70:71], v[146:147], v[70:71]
	v_pk_mul_f32 v[68:69], v[74:75], v[68:69]
	v_pk_mul_f32 v[66:67], v[146:147], v[66:67]
	s_and_b64 vcc, exec, s[4:5]
	v_cvt_pk_bf16_f32 v76, v70, v71
	v_cvt_pk_bf16_f32 v77, v72, v73
	v_cvt_pk_bf16_f32 v78, v66, v67
	v_cvt_pk_bf16_f32 v79, v68, v69
	global_store_dwordx4 v[84:85], v[76:79], off offset:256 sc1
	s_cbranch_vccnz .LBB0_236
	global_store_dwordx4 v[82:83], v[70:73], off offset:512
	global_store_dwordx4 v[82:83], v[66:69], off offset:528
.LBB0_236:
	s_nop 1
	v_lshlrev_b64 v[66:67], 9, v[148:149]
	v_or_b32_e32 v66, v66, v161
	s_mov_b64 s[48:49], 0x10000
	v_lshl_add_u64 v[66:67], v[66:67], 0, s[48:49]
	v_lshl_add_u64 v[68:69], v[66:67], 1, s[76:77]
	v_lshl_add_u64 v[66:67], v[66:67], 2, s[78:79]
	v_pk_mul_f32 v[64:65], v[74:75], v[64:65]
	v_pk_mul_f32 v[62:63], v[146:147], v[62:63]
	v_pk_mul_f32 v[60:61], v[74:75], v[60:61]
	v_pk_mul_f32 v[58:59], v[146:147], v[58:59]
	s_and_b64 vcc, exec, s[4:5]
	v_cvt_pk_bf16_f32 v70, v62, v63
	v_cvt_pk_bf16_f32 v71, v64, v65
	v_cvt_pk_bf16_f32 v72, v58, v59
	v_cvt_pk_bf16_f32 v73, v60, v61
	global_store_dwordx4 v[68:69], v[70:73], off sc1
	s_cbranch_vccnz .LBB0_238
	global_store_dwordx4 v[66:67], v[62:65], off
	global_store_dwordx4 v[66:67], v[58:61], off offset:16
.LBB0_238:
	s_nop 1
	v_mov_b32_e32 v58, v146
	v_mov_b32_e32 v59, v146
	v_pk_mul_f32 v[56:57], v[58:59], v[56:57]
	v_pk_mul_f32 v[54:55], v[146:147], v[54:55]
	v_pk_mul_f32 v[52:53], v[58:59], v[52:53]
	v_pk_mul_f32 v[50:51], v[146:147], v[50:51]
	s_and_b64 vcc, exec, s[4:5]
	v_cvt_pk_bf16_f32 v60, v54, v55
	v_cvt_pk_bf16_f32 v61, v56, v57
	v_cvt_pk_bf16_f32 v62, v50, v51
	v_cvt_pk_bf16_f32 v63, v52, v53
	global_store_dwordx4 v[68:69], v[60:63], off offset:256 sc1
	s_cbranch_vccnz .LBB0_240
	global_store_dwordx4 v[66:67], v[54:57], off offset:512
	global_store_dwordx4 v[66:67], v[50:53], off offset:528
.LBB0_240:
	s_nop 1
	v_lshlrev_b64 v[50:51], 9, v[148:149]
	v_or_b32_e32 v50, v50, v161
	s_mov_b64 s[48:49], 0x12000
	v_lshl_add_u64 v[50:51], v[50:51], 0, s[48:49]
	v_lshl_add_u64 v[52:53], v[50:51], 1, s[76:77]
	v_lshl_add_u64 v[50:51], v[50:51], 2, s[78:79]
	v_pk_mul_f32 v[48:49], v[58:59], v[48:49]
	v_pk_mul_f32 v[46:47], v[146:147], v[46:47]
	v_pk_mul_f32 v[44:45], v[58:59], v[44:45]
	v_pk_mul_f32 v[42:43], v[146:147], v[42:43]
	s_and_b64 vcc, exec, s[4:5]
	v_cvt_pk_bf16_f32 v54, v46, v47
	v_cvt_pk_bf16_f32 v55, v48, v49
	v_cvt_pk_bf16_f32 v56, v42, v43
	v_cvt_pk_bf16_f32 v57, v44, v45
	global_store_dwordx4 v[52:53], v[54:57], off sc1
	s_cbranch_vccnz .LBB0_242
	global_store_dwordx4 v[50:51], v[46:49], off
	global_store_dwordx4 v[50:51], v[42:45], off offset:16
.LBB0_242:
	s_nop 1
	v_mov_b32_e32 v42, v146
	v_mov_b32_e32 v43, v146
	v_pk_mul_f32 v[40:41], v[42:43], v[40:41]
	v_pk_mul_f32 v[38:39], v[146:147], v[38:39]
	v_pk_mul_f32 v[36:37], v[42:43], v[36:37]
	v_pk_mul_f32 v[34:35], v[146:147], v[34:35]
	s_and_b64 vcc, exec, s[4:5]
	v_cvt_pk_bf16_f32 v44, v38, v39
	v_cvt_pk_bf16_f32 v45, v40, v41
	v_cvt_pk_bf16_f32 v46, v34, v35
	v_cvt_pk_bf16_f32 v47, v36, v37
	global_store_dwordx4 v[52:53], v[44:47], off offset:256 sc1
	s_cbranch_vccnz .LBB0_244
	global_store_dwordx4 v[50:51], v[38:41], off offset:512
	global_store_dwordx4 v[50:51], v[34:37], off offset:528
.LBB0_244:
	s_nop 1
	v_lshlrev_b64 v[34:35], 9, v[148:149]
	v_or_b32_e32 v34, v34, v161
	s_mov_b64 s[48:49], 0x14000
	v_lshl_add_u64 v[34:35], v[34:35], 0, s[48:49]
	v_lshl_add_u64 v[36:37], v[34:35], 1, s[76:77]
	v_lshl_add_u64 v[34:35], v[34:35], 2, s[78:79]
	v_pk_mul_f32 v[32:33], v[42:43], v[32:33]
	v_pk_mul_f32 v[30:31], v[146:147], v[30:31]
	v_pk_mul_f32 v[28:29], v[42:43], v[28:29]
	v_pk_mul_f32 v[26:27], v[146:147], v[26:27]
	s_and_b64 vcc, exec, s[4:5]
	v_cvt_pk_bf16_f32 v38, v30, v31
	v_cvt_pk_bf16_f32 v39, v32, v33
	v_cvt_pk_bf16_f32 v40, v26, v27
	v_cvt_pk_bf16_f32 v41, v28, v29
	global_store_dwordx4 v[36:37], v[38:41], off sc1
	s_cbranch_vccnz .LBB0_246
	global_store_dwordx4 v[34:35], v[30:33], off
	global_store_dwordx4 v[34:35], v[26:29], off offset:16
.LBB0_246:
	s_nop 1
	v_mov_b32_e32 v26, v146
	v_mov_b32_e32 v27, v146
	v_pk_mul_f32 v[24:25], v[26:27], v[24:25]
	v_pk_mul_f32 v[22:23], v[146:147], v[22:23]
	v_pk_mul_f32 v[20:21], v[26:27], v[20:21]
	v_pk_mul_f32 v[18:19], v[146:147], v[18:19]
	s_and_b64 vcc, exec, s[4:5]
	v_cvt_pk_bf16_f32 v28, v22, v23
	v_cvt_pk_bf16_f32 v29, v24, v25
	v_cvt_pk_bf16_f32 v30, v18, v19
	v_cvt_pk_bf16_f32 v31, v20, v21
	global_store_dwordx4 v[36:37], v[28:31], off offset:256 sc1
	s_cbranch_vccnz .LBB0_248
	global_store_dwordx4 v[34:35], v[22:25], off offset:512
	global_store_dwordx4 v[34:35], v[18:21], off offset:528
.LBB0_248:
	s_nop 1
	v_lshlrev_b64 v[18:19], 9, v[148:149]
	v_or_b32_e32 v18, v18, v161
	s_mov_b64 s[48:49], 0x16000
	v_lshl_add_u64 v[18:19], v[18:19], 0, s[48:49]
	v_lshl_add_u64 v[20:21], v[18:19], 1, s[76:77]
	v_lshl_add_u64 v[18:19], v[18:19], 2, s[78:79]
	v_pk_mul_f32 v[16:17], v[26:27], v[16:17]
	v_pk_mul_f32 v[14:15], v[146:147], v[14:15]
	v_pk_mul_f32 v[12:13], v[26:27], v[12:13]
	v_pk_mul_f32 v[10:11], v[146:147], v[10:11]
	s_and_b64 vcc, exec, s[4:5]
	v_cvt_pk_bf16_f32 v22, v14, v15
	v_cvt_pk_bf16_f32 v23, v16, v17
	v_cvt_pk_bf16_f32 v24, v10, v11
	v_cvt_pk_bf16_f32 v25, v12, v13
	global_store_dwordx4 v[20:21], v[22:25], off sc1
	s_cbranch_vccnz .LBB0_250
	global_store_dwordx4 v[18:19], v[14:17], off
	global_store_dwordx4 v[18:19], v[10:13], off offset:16
.LBB0_250:
	s_nop 1
	v_mov_b32_e32 v10, v146
	v_mov_b32_e32 v11, v146
	v_pk_mul_f32 v[8:9], v[10:11], v[8:9]
	v_pk_mul_f32 v[6:7], v[146:147], v[6:7]
	v_pk_mul_f32 v[4:5], v[10:11], v[4:5]
	v_pk_mul_f32 v[2:3], v[146:147], v[2:3]
	s_and_b64 vcc, exec, s[4:5]
	v_cvt_pk_bf16_f32 v10, v6, v7
	v_cvt_pk_bf16_f32 v11, v8, v9
	v_cvt_pk_bf16_f32 v12, v2, v3
	v_cvt_pk_bf16_f32 v13, v4, v5
	global_store_dwordx4 v[20:21], v[10:13], off offset:256 sc1
	s_cbranch_vccnz .LBB0_252
	global_store_dwordx4 v[18:19], v[6:9], off offset:512
	global_store_dwordx4 v[18:19], v[2:5], off offset:528

.LBB0_1134:
	s_lshl_b32 s39, s46, 8
	s_and_b32 s39, s39, 0x100
	s_cmp_eq_u32 s37, 1
	ds_read_b32 v152, v157
	s_cselect_b64 vcc, -1, 0
	v_lshl_add_u32 v148, s44, 8, v156
	v_cndmask_b32_e32 v149, 1.0, v163, vcc
	v_cndmask_b32_e64 v166, v149, v164, s[4:5]
	v_ashrrev_i32_e32 v149, 31, v148
	v_or_b32_e32 v165, s39, v159
	v_lshlrev_b64 v[150:151], 9, v[148:149]
	s_cmp_lg_u64 s[58:59], 0
	v_or_b32_e32 v150, v150, v165
	s_waitcnt lgkmcnt(0)
	v_mul_f32_e32 v154, v166, v152
	s_cselect_b64 s[44:45], -1, 0
	s_cmp_eq_u64 s[58:59], 0
	v_lshl_add_u64 v[152:153], v[150:151], 1, s[48:49]
	v_lshl_add_u64 v[150:151], v[150:151], 2, s[58:59]
	v_pk_mul_f32 v[130:131], v[130:131], v[154:155] op_sel_hi:[1,0]
	v_pk_mul_f32 v[128:129], v[128:129], v[154:155] op_sel_hi:[1,0]
	v_pk_mul_f32 v[126:127], v[126:127], v[154:155] op_sel_hi:[1,0]
	v_pk_mul_f32 v[124:125], v[124:125], v[154:155] op_sel_hi:[1,0]
	v_cvt_pk_bf16_f32 v168, v128, v129
	v_cvt_pk_bf16_f32 v169, v130, v131
	s_nop 0
	v_cvt_pk_bf16_f32 v170, v124, v125
	v_cvt_pk_bf16_f32 v171, v126, v127
	global_store_dwordx4 v[152:153], v[168:171], off sc1
	s_cbranch_scc1 .LBB0_1136
	global_store_dwordx4 v[150:151], v[128:131], off
	global_store_dwordx4 v[150:151], v[124:127], off offset:16
.LBB0_1136:
	v_mov_b32_e32 v155, v154
	s_nop 0
	v_mov_b32_e32 v124, v154
	v_mov_b32_e32 v125, v154
	v_cndmask_b32_e64 v128, 0, 1, s[44:45]
	v_pk_mul_f32 v[122:123], v[122:123], v[124:125]
	v_pk_mul_f32 v[120:121], v[120:121], v[154:155]
	v_pk_mul_f32 v[118:119], v[118:119], v[124:125]
	v_pk_mul_f32 v[116:117], v[116:117], v[154:155]
	v_cmp_ne_u32_e64 s[4:5], 1, v128
	s_andn2_b64 vcc, exec, s[44:45]
	v_cvt_pk_bf16_f32 v124, v120, v121
	v_cvt_pk_bf16_f32 v125, v122, v123
	v_cvt_pk_bf16_f32 v126, v116, v117
	v_cvt_pk_bf16_f32 v127, v118, v119
	global_store_dwordx4 v[152:153], v[124:127], off offset:256 sc1
	s_cbranch_vccnz .LBB0_1138
	global_store_dwordx4 v[150:151], v[120:123], off offset:512
	global_store_dwordx4 v[150:151], v[116:119], off offset:528
.LBB0_1138:
	ds_read_b32 v118, v157 offset:64
	s_nop 0
	v_or_b32_e32 v116, 16, v148
	v_ashrrev_i32_e32 v117, 31, v116
	v_lshlrev_b64 v[116:117], 9, v[116:117]
	v_or_b32_e32 v116, v116, v165
	s_waitcnt lgkmcnt(0)
	v_mul_f32_e32 v120, v166, v118
	v_lshl_add_u64 v[118:119], v[116:117], 1, s[48:49]
	v_lshl_add_u64 v[116:117], v[116:117], 2, s[58:59]
	v_pk_mul_f32 v[114:115], v[114:115], v[120:121] op_sel_hi:[1,0]
	v_pk_mul_f32 v[112:113], v[112:113], v[120:121] op_sel_hi:[1,0]
	v_pk_mul_f32 v[110:111], v[110:111], v[120:121] op_sel_hi:[1,0]
	v_pk_mul_f32 v[108:109], v[108:109], v[120:121] op_sel_hi:[1,0]
	s_and_b64 vcc, exec, s[4:5]
	v_cvt_pk_bf16_f32 v122, v112, v113
	v_cvt_pk_bf16_f32 v123, v114, v115
	v_cvt_pk_bf16_f32 v124, v108, v109
	v_cvt_pk_bf16_f32 v125, v110, v111
	global_store_dwordx4 v[118:119], v[122:125], off sc1
	s_cbranch_vccnz .LBB0_1140
	global_store_dwordx4 v[116:117], v[112:115], off
	global_store_dwordx4 v[116:117], v[108:111], off offset:16
.LBB0_1140:
	v_mov_b32_e32 v121, v120
	s_nop 0
	v_mov_b32_e32 v108, v120
	v_mov_b32_e32 v109, v120
	v_pk_mul_f32 v[106:107], v[106:107], v[108:109]
	v_pk_mul_f32 v[104:105], v[104:105], v[120:121]
	v_pk_mul_f32 v[102:103], v[102:103], v[108:109]
	v_pk_mul_f32 v[100:101], v[100:101], v[120:121]
	s_and_b64 vcc, exec, s[4:5]
	v_cvt_pk_bf16_f32 v108, v104, v105
	v_cvt_pk_bf16_f32 v109, v106, v107
	v_cvt_pk_bf16_f32 v110, v100, v101
	v_cvt_pk_bf16_f32 v111, v102, v103
	global_store_dwordx4 v[118:119], v[108:111], off offset:256 sc1
	s_cbranch_vccnz .LBB0_1142
	global_store_dwordx4 v[116:117], v[104:107], off offset:512
	global_store_dwordx4 v[116:117], v[100:103], off offset:528
.LBB0_1142:
	ds_read_b32 v102, v157 offset:128
	s_nop 0
	v_or_b32_e32 v100, 32, v148
	v_ashrrev_i32_e32 v101, 31, v100
	v_lshlrev_b64 v[100:101], 9, v[100:101]
	v_or_b32_e32 v100, v100, v165
	s_waitcnt lgkmcnt(0)
	v_mul_f32_e32 v104, v166, v102
	v_lshl_add_u64 v[102:103], v[100:101], 1, s[48:49]
	v_lshl_add_u64 v[100:101], v[100:101], 2, s[58:59]
	v_pk_mul_f32 v[98:99], v[98:99], v[104:105] op_sel_hi:[1,0]
	v_pk_mul_f32 v[96:97], v[96:97], v[104:105] op_sel_hi:[1,0]
	v_pk_mul_f32 v[94:95], v[94:95], v[104:105] op_sel_hi:[1,0]
	v_pk_mul_f32 v[92:93], v[92:93], v[104:105] op_sel_hi:[1,0]
	s_and_b64 vcc, exec, s[4:5]
	v_cvt_pk_bf16_f32 v106, v96, v97
	v_cvt_pk_bf16_f32 v107, v98, v99
	v_cvt_pk_bf16_f32 v108, v92, v93
	v_cvt_pk_bf16_f32 v109, v94, v95
	global_store_dwordx4 v[102:103], v[106:109], off sc1
	s_cbranch_vccnz .LBB0_1144
	global_store_dwordx4 v[100:101], v[96:99], off
	global_store_dwordx4 v[100:101], v[92:95], off offset:16
.LBB0_1144:
	v_mov_b32_e32 v105, v104
	s_nop 0
	v_mov_b32_e32 v92, v104
	v_mov_b32_e32 v93, v104
	v_pk_mul_f32 v[90:91], v[90:91], v[92:93]
	v_pk_mul_f32 v[88:89], v[88:89], v[104:105]
	v_pk_mul_f32 v[86:87], v[86:87], v[92:93]
	v_pk_mul_f32 v[84:85], v[84:85], v[104:105]
	s_and_b64 vcc, exec, s[4:5]
	v_cvt_pk_bf16_f32 v92, v88, v89
	v_cvt_pk_bf16_f32 v93, v90, v91
	v_cvt_pk_bf16_f32 v94, v84, v85
	v_cvt_pk_bf16_f32 v95, v86, v87
	global_store_dwordx4 v[102:103], v[92:95], off offset:256 sc1
	s_cbranch_vccnz .LBB0_1146
	global_store_dwordx4 v[100:101], v[88:91], off offset:512
	global_store_dwordx4 v[100:101], v[84:87], off offset:528
.LBB0_1146:
	ds_read_b32 v86, v157 offset:192
	s_nop 0
	v_or_b32_e32 v84, 48, v148
	v_ashrrev_i32_e32 v85, 31, v84
	v_lshlrev_b64 v[84:85], 9, v[84:85]
	v_or_b32_e32 v84, v84, v165
	s_waitcnt lgkmcnt(0)
	v_mul_f32_e32 v88, v166, v86
	v_lshl_add_u64 v[86:87], v[84:85], 1, s[48:49]
	v_lshl_add_u64 v[84:85], v[84:85], 2, s[58:59]
	v_pk_mul_f32 v[82:83], v[82:83], v[88:89] op_sel_hi:[1,0]
	v_pk_mul_f32 v[80:81], v[80:81], v[88:89] op_sel_hi:[1,0]
	v_pk_mul_f32 v[78:79], v[78:79], v[88:89] op_sel_hi:[1,0]
	v_pk_mul_f32 v[76:77], v[76:77], v[88:89] op_sel_hi:[1,0]
	s_and_b64 vcc, exec, s[4:5]
	v_cvt_pk_bf16_f32 v90, v80, v81
	v_cvt_pk_bf16_f32 v91, v82, v83
	v_cvt_pk_bf16_f32 v92, v76, v77
	v_cvt_pk_bf16_f32 v93, v78, v79
	global_store_dwordx4 v[86:87], v[90:93], off sc1
	s_cbranch_vccnz .LBB0_1148
	global_store_dwordx4 v[84:85], v[80:83], off
	global_store_dwordx4 v[84:85], v[76:79], off offset:16
.LBB0_1148:
	v_mov_b32_e32 v89, v88
	s_nop 0
	v_mov_b32_e32 v76, v88
	v_mov_b32_e32 v77, v88
	v_pk_mul_f32 v[74:75], v[74:75], v[76:77]
	v_pk_mul_f32 v[72:73], v[72:73], v[88:89]
	v_pk_mul_f32 v[70:71], v[70:71], v[76:77]
	v_pk_mul_f32 v[68:69], v[68:69], v[88:89]
	s_and_b64 vcc, exec, s[4:5]
	v_cvt_pk_bf16_f32 v76, v72, v73
	v_cvt_pk_bf16_f32 v77, v74, v75
	v_cvt_pk_bf16_f32 v78, v68, v69
	v_cvt_pk_bf16_f32 v79, v70, v71
	global_store_dwordx4 v[86:87], v[76:79], off offset:256 sc1
	s_cbranch_vccnz .LBB0_1150
	global_store_dwordx4 v[84:85], v[72:75], off offset:512
	global_store_dwordx4 v[84:85], v[68:71], off offset:528
.LBB0_1150:
	ds_read_b32 v72, v158
	s_nop 0
	v_lshlrev_b64 v[68:69], 9, v[148:149]
	v_or_b32_e32 v68, v68, v165
	v_lshl_add_u64 v[68:69], v[68:69], 0, s[26:27]
	v_lshl_add_u64 v[70:71], v[68:69], 1, s[48:49]
	s_waitcnt lgkmcnt(0)
	v_mul_f32_e32 v72, v166, v72
	v_lshl_add_u64 v[68:69], v[68:69], 2, s[58:59]
	v_pk_mul_f32 v[66:67], v[66:67], v[72:73] op_sel_hi:[1,0]
	v_pk_mul_f32 v[64:65], v[64:65], v[72:73] op_sel_hi:[1,0]
	v_pk_mul_f32 v[62:63], v[62:63], v[72:73] op_sel_hi:[1,0]
	v_pk_mul_f32 v[60:61], v[60:61], v[72:73] op_sel_hi:[1,0]
	s_and_b64 vcc, exec, s[4:5]
	v_cvt_pk_bf16_f32 v74, v64, v65
	v_cvt_pk_bf16_f32 v75, v66, v67
	v_cvt_pk_bf16_f32 v76, v60, v61
	v_cvt_pk_bf16_f32 v77, v62, v63
	global_store_dwordx4 v[70:71], v[74:77], off sc1
	s_cbranch_vccnz .LBB0_1152
	global_store_dwordx4 v[68:69], v[64:67], off
	global_store_dwordx4 v[68:69], v[60:63], off offset:16
.LBB0_1152:
	v_mov_b32_e32 v73, v72
	s_nop 0
	v_mov_b32_e32 v60, v72
	v_mov_b32_e32 v61, v72
	v_pk_mul_f32 v[58:59], v[58:59], v[60:61]
	v_pk_mul_f32 v[56:57], v[56:57], v[72:73]
	v_pk_mul_f32 v[54:55], v[54:55], v[60:61]
	v_pk_mul_f32 v[52:53], v[52:53], v[72:73]
	s_and_b64 vcc, exec, s[4:5]
	v_cvt_pk_bf16_f32 v60, v56, v57
	v_cvt_pk_bf16_f32 v61, v58, v59
	v_cvt_pk_bf16_f32 v62, v52, v53
	v_cvt_pk_bf16_f32 v63, v54, v55
	global_store_dwordx4 v[70:71], v[60:63], off offset:256 sc1
	s_cbranch_vccnz .LBB0_1154
	global_store_dwordx4 v[68:69], v[56:59], off offset:512
	global_store_dwordx4 v[68:69], v[52:55], off offset:528
.LBB0_1154:
	ds_read_b32 v56, v157 offset:576
	s_nop 0
	v_lshlrev_b64 v[52:53], 9, v[148:149]
	v_or_b32_e32 v52, v52, v165
	v_lshl_add_u64 v[52:53], v[52:53], 0, s[28:29]
	v_lshl_add_u64 v[54:55], v[52:53], 1, s[48:49]
	s_waitcnt lgkmcnt(0)
	v_mul_f32_e32 v56, v166, v56
	v_lshl_add_u64 v[52:53], v[52:53], 2, s[58:59]
	v_pk_mul_f32 v[50:51], v[50:51], v[56:57] op_sel_hi:[1,0]
	v_pk_mul_f32 v[48:49], v[48:49], v[56:57] op_sel_hi:[1,0]
	v_pk_mul_f32 v[46:47], v[46:47], v[56:57] op_sel_hi:[1,0]
	v_pk_mul_f32 v[44:45], v[44:45], v[56:57] op_sel_hi:[1,0]
	s_and_b64 vcc, exec, s[4:5]
	v_cvt_pk_bf16_f32 v58, v48, v49
	v_cvt_pk_bf16_f32 v59, v50, v51
	v_cvt_pk_bf16_f32 v60, v44, v45
	v_cvt_pk_bf16_f32 v61, v46, v47
	global_store_dwordx4 v[54:55], v[58:61], off sc1
	s_cbranch_vccnz .LBB0_1156
	global_store_dwordx4 v[52:53], v[48:51], off
	global_store_dwordx4 v[52:53], v[44:47], off offset:16
.LBB0_1156:
	v_mov_b32_e32 v57, v56
	s_nop 0
	v_mov_b32_e32 v44, v56
	v_mov_b32_e32 v45, v56
	v_pk_mul_f32 v[42:43], v[42:43], v[44:45]
	v_pk_mul_f32 v[40:41], v[40:41], v[56:57]
	v_pk_mul_f32 v[38:39], v[38:39], v[44:45]
	v_pk_mul_f32 v[36:37], v[36:37], v[56:57]
	s_and_b64 vcc, exec, s[4:5]
	v_cvt_pk_bf16_f32 v44, v40, v41
	v_cvt_pk_bf16_f32 v45, v42, v43
	v_cvt_pk_bf16_f32 v46, v36, v37
	v_cvt_pk_bf16_f32 v47, v38, v39
	global_store_dwordx4 v[54:55], v[44:47], off offset:256 sc1
	s_cbranch_vccnz .LBB0_1158
	global_store_dwordx4 v[52:53], v[40:43], off offset:512
	global_store_dwordx4 v[52:53], v[36:39], off offset:528
.LBB0_1158:
	ds_read_b32 v40, v157 offset:640
	s_nop 0
	v_lshlrev_b64 v[36:37], 9, v[148:149]
	v_or_b32_e32 v36, v36, v165
	v_lshl_add_u64 v[36:37], v[36:37], 0, s[30:31]
	v_lshl_add_u64 v[38:39], v[36:37], 1, s[48:49]
	s_waitcnt lgkmcnt(0)
	v_mul_f32_e32 v40, v166, v40
	v_lshl_add_u64 v[36:37], v[36:37], 2, s[58:59]
	v_pk_mul_f32 v[34:35], v[34:35], v[40:41] op_sel_hi:[1,0]
	v_pk_mul_f32 v[32:33], v[32:33], v[40:41] op_sel_hi:[1,0]
	v_pk_mul_f32 v[30:31], v[30:31], v[40:41] op_sel_hi:[1,0]
	v_pk_mul_f32 v[28:29], v[28:29], v[40:41] op_sel_hi:[1,0]
	s_and_b64 vcc, exec, s[4:5]
	v_cvt_pk_bf16_f32 v42, v32, v33
	v_cvt_pk_bf16_f32 v43, v34, v35
	v_cvt_pk_bf16_f32 v44, v28, v29
	v_cvt_pk_bf16_f32 v45, v30, v31
	global_store_dwordx4 v[38:39], v[42:45], off sc1
	s_cbranch_vccnz .LBB0_1160
	global_store_dwordx4 v[36:37], v[32:35], off
	global_store_dwordx4 v[36:37], v[28:31], off offset:16
.LBB0_1160:
	v_mov_b32_e32 v41, v40
	s_nop 0
	v_mov_b32_e32 v28, v40
	v_mov_b32_e32 v29, v40
	v_pk_mul_f32 v[26:27], v[26:27], v[28:29]
	v_pk_mul_f32 v[24:25], v[24:25], v[40:41]
	v_pk_mul_f32 v[22:23], v[22:23], v[28:29]
	v_pk_mul_f32 v[20:21], v[20:21], v[40:41]
	s_and_b64 vcc, exec, s[4:5]
	v_cvt_pk_bf16_f32 v28, v24, v25
	v_cvt_pk_bf16_f32 v29, v26, v27
	v_cvt_pk_bf16_f32 v30, v20, v21
	v_cvt_pk_bf16_f32 v31, v22, v23
	global_store_dwordx4 v[38:39], v[28:31], off offset:256 sc1
	s_cbranch_vccnz .LBB0_1162
	global_store_dwordx4 v[36:37], v[24:27], off offset:512
	global_store_dwordx4 v[36:37], v[20:23], off offset:528
.LBB0_1162:
	ds_read_b32 v24, v157 offset:704
	s_nop 0
	v_lshlrev_b64 v[20:21], 9, v[148:149]
	v_or_b32_e32 v20, v20, v165
	v_lshl_add_u64 v[20:21], v[20:21], 0, s[34:35]
	v_lshl_add_u64 v[22:23], v[20:21], 1, s[48:49]
	s_waitcnt lgkmcnt(0)
	v_mul_f32_e32 v24, v166, v24
	v_lshl_add_u64 v[20:21], v[20:21], 2, s[58:59]
	v_pk_mul_f32 v[18:19], v[18:19], v[24:25] op_sel_hi:[1,0]
	v_pk_mul_f32 v[16:17], v[16:17], v[24:25] op_sel_hi:[1,0]
	v_pk_mul_f32 v[14:15], v[14:15], v[24:25] op_sel_hi:[1,0]
	v_pk_mul_f32 v[12:13], v[12:13], v[24:25] op_sel_hi:[1,0]
	s_and_b64 vcc, exec, s[4:5]
	v_cvt_pk_bf16_f32 v26, v16, v17
	v_cvt_pk_bf16_f32 v27, v18, v19
	v_cvt_pk_bf16_f32 v28, v12, v13
	v_cvt_pk_bf16_f32 v29, v14, v15
	global_store_dwordx4 v[22:23], v[26:29], off sc1
	s_cbranch_vccnz .LBB0_1164
	global_store_dwordx4 v[20:21], v[16:19], off
	global_store_dwordx4 v[20:21], v[12:15], off offset:16
.LBB0_1164:
	v_mov_b32_e32 v25, v24
	s_nop 0
	v_mov_b32_e32 v12, v24
	v_mov_b32_e32 v13, v24
	v_pk_mul_f32 v[10:11], v[10:11], v[12:13]
	v_pk_mul_f32 v[8:9], v[8:9], v[24:25]
	v_pk_mul_f32 v[6:7], v[6:7], v[12:13]
	v_pk_mul_f32 v[4:5], v[4:5], v[24:25]
	s_and_b64 vcc, exec, s[4:5]
	v_cvt_pk_bf16_f32 v12, v8, v9
	v_cvt_pk_bf16_f32 v13, v10, v11
	v_cvt_pk_bf16_f32 v14, v4, v5
	v_cvt_pk_bf16_f32 v15, v6, v7
	global_store_dwordx4 v[22:23], v[12:15], off offset:256 sc1
	s_cbranch_vccnz .LBB0_1166
	global_store_dwordx4 v[20:21], v[8:11], off offset:512
	global_store_dwordx4 v[20:21], v[4:7], off offset:528

.LBB0_1898:
	s_or_b64 exec, exec, s[4:5]
	v_lshlrev_b64 v[210:211], 2, v[190:191]
	v_lshl_add_u64 v[190:191], s[56:57], 0, v[210:211]
	s_mov_b64 s[0:1], 0x1000
	s_waitcnt vmcnt(0) lgkmcnt(0)
	s_barrier
	v_lshl_add_u64 v[192:193], v[190:191], 0, s[0:1]
	v_add_co_u32_e32 v190, vcc, 0x1000, v190
	global_load_dwordx4 v[202:205], v[192:193], off offset:16
	global_load_dwordx4 v[194:197], v[192:193], off offset:512
	v_addc_co_u32_e32 v191, vcc, 0, v191, vcc
	global_load_dwordx4 v[206:209], v[190:191], off
	s_nop 0
	global_load_dwordx4 v[190:193], v[192:193], off offset:528
	v_lshl_add_u32 v213, v214, 2, 0
	v_add_u32_e32 v242, 0x1000, v213
	ds_read2_b32 v[230:231], v242 offset1:16
	v_add_u32_e32 v212, s8, v214
	v_add_u32_e32 v228, 16, v212
	v_ashrrev_i32_e32 v213, 31, v212
	v_ashrrev_i32_e32 v229, 31, v228
	v_lshlrev_b64 v[232:233], 12, v[212:213]
	v_lshlrev_b64 v[228:229], 12, v[228:229]
	s_waitcnt vmcnt(0)
	v_lshlrev_b32_e32 v216, 16, v200
	v_and_b32_e32 v217, 0xffff0000, v200
	v_lshlrev_b32_e32 v200, 16, v201
	v_and_b32_e32 v201, 0xffff0000, v201
	v_lshlrev_b32_e32 v218, 16, v186
	v_and_b32_e32 v219, 0xffff0000, v186
	v_lshlrev_b32_e32 v186, 16, v187
	v_and_b32_e32 v187, 0xffff0000, v187
	v_lshlrev_b32_e32 v224, 16, v184
	v_and_b32_e32 v225, 0xffff0000, v184
	v_lshlrev_b32_e32 v184, 16, v185
	v_and_b32_e32 v185, 0xffff0000, v185
	v_lshlrev_b32_e32 v226, 16, v178
	v_and_b32_e32 v227, 0xffff0000, v178
	v_lshl_add_u64 v[232:233], s[80:81], 0, v[232:233]
	v_lshl_add_u64 v[228:229], s[80:81], 0, v[228:229]
	s_waitcnt lgkmcnt(0)
	v_mov_b32_e32 v178, v231
	v_lshlrev_b32_e32 v214, 16, v198
	v_and_b32_e32 v215, 0xffff0000, v198
	v_lshlrev_b32_e32 v198, 16, v199
	v_and_b32_e32 v199, 0xffff0000, v199
	v_lshlrev_b32_e32 v220, 16, v188
	v_and_b32_e32 v221, 0xffff0000, v188
	v_lshlrev_b32_e32 v188, 16, v189
	v_and_b32_e32 v189, 0xffff0000, v189
	v_lshlrev_b32_e32 v222, 16, v182
	v_and_b32_e32 v223, 0xffff0000, v182
	v_lshlrev_b32_e32 v182, 16, v183
	v_and_b32_e32 v183, 0xffff0000, v183
	v_lshl_add_u64 v[232:233], v[232:233], 0, v[210:211]
	v_lshl_add_u64 v[228:229], v[228:229], 0, v[210:211]
	v_pk_mul_f32 v[128:129], v[128:129], v[204:205]
	v_pk_mul_f32 v[126:127], v[126:127], v[202:203]
	v_pk_mul_f32 v[234:235], v[112:113], v[196:197]
	v_pk_mul_f32 v[236:237], v[110:111], v[194:195]
	v_pk_mul_f32 v[238:239], v[120:121], v[204:205]
	v_pk_mul_f32 v[240:241], v[118:119], v[202:203]
	v_pk_mul_f32 v[124:125], v[124:125], v[208:209]
	v_pk_mul_f32 v[122:123], v[122:123], v[206:207]
	v_pk_fma_f32 v[112:113], v[128:129], v[230:231], v[200:201] op_sel_hi:[1,0,1]
	v_pk_fma_f32 v[110:111], v[126:127], v[230:231], v[216:217] op_sel_hi:[1,0,1]
	v_pk_fma_f32 v[120:121], v[234:235], v[230:231], v[186:187] op_sel_hi:[1,0,1]
	v_pk_fma_f32 v[118:119], v[236:237], v[230:231], v[218:219] op_sel_hi:[1,0,1]
	v_pk_mul_f32 v[126:127], v[108:109], v[192:193]
	v_pk_mul_f32 v[128:129], v[106:107], v[190:191]
	v_pk_mul_f32 v[186:187], v[116:117], v[208:209]
	v_pk_mul_f32 v[200:201], v[114:115], v[206:207]
	v_pk_fma_f32 v[108:109], v[238:239], v[178:179], v[184:185] op_sel_hi:[1,0,1]
	v_pk_fma_f32 v[106:107], v[240:241], v[178:179], v[224:225] op_sel_hi:[1,0,1]
	v_pk_fma_f32 v[114:115], v[122:123], v[230:231], v[214:215] op_sel_hi:[1,0,1]
	v_pk_fma_f32 v[116:117], v[124:125], v[230:231], v[198:199] op_sel_hi:[1,0,1]
	global_store_dwordx4 v[232:233], v[110:113], off offset:16
	global_store_dwordx4 v[232:233], v[118:121], off offset:512
	v_pk_mul_f32 v[104:105], v[104:105], v[196:197]
	v_pk_fma_f32 v[112:113], v[126:127], v[230:231], v[188:189] op_sel_hi:[1,0,1]
	v_pk_fma_f32 v[110:111], v[128:129], v[230:231], v[220:221] op_sel_hi:[1,0,1]
	v_pk_fma_f32 v[118:119], v[200:201], v[178:179], v[222:223] op_sel_hi:[1,0,1]
	v_pk_fma_f32 v[120:121], v[186:187], v[178:179], v[182:183] op_sel_hi:[1,0,1]
	global_store_dwordx4 v[228:229], v[106:109], off offset:16
	global_store_dwordx4 v[232:233], v[114:117], off
	global_store_dwordx4 v[232:233], v[110:113], off offset:528
	global_store_dwordx4 v[228:229], v[118:121], off
	v_lshlrev_b32_e32 v106, 16, v179
	v_and_b32_e32 v107, 0xffff0000, v179
	v_pk_mul_f32 v[102:103], v[102:103], v[194:195]
	v_lshlrev_b32_e32 v108, 16, v180
	v_and_b32_e32 v109, 0xffff0000, v180
	v_lshlrev_b32_e32 v110, 16, v181
	v_and_b32_e32 v111, 0xffff0000, v181
	v_pk_fma_f32 v[104:105], v[104:105], v[178:179], v[106:107] op_sel_hi:[1,0,1]
	v_pk_fma_f32 v[102:103], v[102:103], v[178:179], v[226:227] op_sel_hi:[1,0,1]
	v_pk_mul_f32 v[100:101], v[100:101], v[192:193]
	v_pk_mul_f32 v[98:99], v[98:99], v[190:191]
	v_pk_fma_f32 v[100:101], v[100:101], v[178:179], v[110:111] op_sel_hi:[1,0,1]
	v_pk_fma_f32 v[98:99], v[98:99], v[178:179], v[108:109] op_sel_hi:[1,0,1]
	global_store_dwordx4 v[228:229], v[102:105], off offset:512
	global_store_dwordx4 v[228:229], v[98:101], off offset:528
	ds_read2_b32 v[98:99], v242 offset0:32 offset1:48
	v_lshlrev_b32_e32 v102, 16, v174
	v_add_u32_e32 v100, 32, v212
	v_ashrrev_i32_e32 v101, 31, v100
	v_lshlrev_b64 v[100:101], 12, v[100:101]
	v_and_b32_e32 v103, 0xffff0000, v174
	v_lshlrev_b32_e32 v104, 16, v175
	v_and_b32_e32 v105, 0xffff0000, v175
	v_lshlrev_b32_e32 v106, 16, v176
	v_and_b32_e32 v107, 0xffff0000, v176
	v_lshlrev_b32_e32 v108, 16, v177
	v_and_b32_e32 v109, 0xffff0000, v177
	v_pk_mul_f32 v[96:97], v[96:97], v[208:209]
	v_pk_mul_f32 v[94:95], v[94:95], v[206:207]
	v_pk_mul_f32 v[92:93], v[92:93], v[204:205]
	v_pk_mul_f32 v[90:91], v[90:91], v[202:203]
	v_lshl_add_u64 v[100:101], s[80:81], 0, v[100:101]
	s_waitcnt lgkmcnt(0)
	v_pk_fma_f32 v[94:95], v[94:95], v[98:99], v[102:103] op_sel_hi:[1,0,1]
	v_pk_fma_f32 v[96:97], v[96:97], v[98:99], v[104:105] op_sel_hi:[1,0,1]
	v_pk_fma_f32 v[92:93], v[92:93], v[98:99], v[108:109] op_sel_hi:[1,0,1]
	v_pk_fma_f32 v[90:91], v[90:91], v[98:99], v[106:107] op_sel_hi:[1,0,1]
	v_lshl_add_u64 v[100:101], v[100:101], 0, v[210:211]
	global_store_dwordx4 v[100:101], v[94:97], off
	global_store_dwordx4 v[100:101], v[90:93], off offset:16
	v_pk_mul_f32 v[88:89], v[88:89], v[196:197]
	v_lshlrev_b32_e32 v94, 16, v172
	v_lshlrev_b32_e32 v90, 16, v170
	v_and_b32_e32 v91, 0xffff0000, v170
	v_lshlrev_b32_e32 v92, 16, v171
	v_and_b32_e32 v93, 0xffff0000, v171
	v_and_b32_e32 v95, 0xffff0000, v172
	v_pk_mul_f32 v[86:87], v[86:87], v[194:195]
	v_pk_mul_f32 v[82:83], v[82:83], v[190:191]
	v_lshlrev_b32_e32 v96, 16, v173
	v_and_b32_e32 v97, 0xffff0000, v173
	v_pk_fma_f32 v[88:89], v[88:89], v[98:99], v[92:93] op_sel_hi:[1,0,1]
	v_pk_fma_f32 v[86:87], v[86:87], v[98:99], v[90:91] op_sel_hi:[1,0,1]
	v_pk_mul_f32 v[84:85], v[84:85], v[192:193]
	v_pk_fma_f32 v[82:83], v[82:83], v[98:99], v[94:95] op_sel_hi:[1,0,1]
	v_pk_fma_f32 v[84:85], v[84:85], v[98:99], v[96:97] op_sel_hi:[1,0,1]
	global_store_dwordx4 v[100:101], v[86:89], off offset:512
	global_store_dwordx4 v[100:101], v[82:85], off offset:528
	v_lshlrev_b32_e32 v90, 16, v169
	v_lshlrev_b32_e32 v86, 16, v167
	v_add_u32_e32 v82, 48, v212
	v_ashrrev_i32_e32 v83, 31, v82
	v_lshlrev_b64 v[82:83], 12, v[82:83]
	v_lshlrev_b32_e32 v84, 16, v166
	v_and_b32_e32 v85, 0xffff0000, v166
	v_and_b32_e32 v87, 0xffff0000, v167
	v_lshlrev_b32_e32 v88, 16, v168
	v_and_b32_e32 v89, 0xffff0000, v168
	v_and_b32_e32 v91, 0xffff0000, v169
	v_pk_mul_f32 v[80:81], v[80:81], v[208:209]
	v_pk_mul_f32 v[78:79], v[78:79], v[206:207]
	v_mov_b32_e32 v92, v99
	v_pk_mul_f32 v[76:77], v[76:77], v[204:205]
	v_pk_mul_f32 v[74:75], v[74:75], v[202:203]
	v_lshl_add_u64 v[82:83], s[80:81], 0, v[82:83]
	v_pk_fma_f32 v[78:79], v[78:79], v[92:93], v[84:85] op_sel_hi:[1,0,1]
	v_pk_fma_f32 v[80:81], v[80:81], v[92:93], v[86:87] op_sel_hi:[1,0,1]
	v_pk_fma_f32 v[76:77], v[76:77], v[92:93], v[90:91] op_sel_hi:[1,0,1]
	v_pk_fma_f32 v[74:75], v[74:75], v[92:93], v[88:89] op_sel_hi:[1,0,1]
	v_lshl_add_u64 v[82:83], v[82:83], 0, v[210:211]
	global_store_dwordx4 v[82:83], v[78:81], off
	global_store_dwordx4 v[82:83], v[74:77], off offset:16
	v_pk_mul_f32 v[72:73], v[72:73], v[196:197]
	v_pk_mul_f32 v[70:71], v[70:71], v[194:195]
	v_lshlrev_b32_e32 v74, 16, v162
	v_and_b32_e32 v75, 0xffff0000, v162
	v_lshlrev_b32_e32 v76, 16, v163
	v_and_b32_e32 v77, 0xffff0000, v163
	v_lshlrev_b32_e32 v78, 16, v164
	v_and_b32_e32 v79, 0xffff0000, v164
	v_lshlrev_b32_e32 v80, 16, v165
	v_and_b32_e32 v81, 0xffff0000, v165
	v_pk_fma_f32 v[72:73], v[72:73], v[92:93], v[76:77] op_sel_hi:[1,0,1]
	v_pk_fma_f32 v[70:71], v[70:71], v[92:93], v[74:75] op_sel_hi:[1,0,1]
	v_pk_mul_f32 v[68:69], v[68:69], v[192:193]
	v_pk_mul_f32 v[66:67], v[66:67], v[190:191]
	v_pk_fma_f32 v[68:69], v[68:69], v[92:93], v[80:81] op_sel_hi:[1,0,1]
	v_pk_fma_f32 v[66:67], v[66:67], v[92:93], v[78:79] op_sel_hi:[1,0,1]
	global_store_dwordx4 v[82:83], v[70:73], off offset:512
	global_store_dwordx4 v[82:83], v[66:69], off offset:528
	ds_read2_b32 v[66:67], v242 offset0:128 offset1:144
	v_lshlrev_b32_e32 v70, 16, v158
	v_add_u32_e32 v68, 0x80, v212
	v_ashrrev_i32_e32 v69, 31, v68
	v_lshlrev_b64 v[68:69], 12, v[68:69]
	v_and_b32_e32 v71, 0xffff0000, v158
	v_lshlrev_b32_e32 v72, 16, v159
	v_and_b32_e32 v73, 0xffff0000, v159
	v_lshlrev_b32_e32 v74, 16, v160
	v_and_b32_e32 v75, 0xffff0000, v160
	v_lshlrev_b32_e32 v76, 16, v161
	v_and_b32_e32 v77, 0xffff0000, v161
	v_pk_mul_f32 v[64:65], v[64:65], v[208:209]
	v_pk_mul_f32 v[62:63], v[62:63], v[206:207]
	v_pk_mul_f32 v[60:61], v[60:61], v[204:205]
	v_pk_mul_f32 v[58:59], v[58:59], v[202:203]
	v_lshl_add_u64 v[68:69], s[80:81], 0, v[68:69]
	s_waitcnt lgkmcnt(0)
	v_pk_fma_f32 v[62:63], v[62:63], v[66:67], v[70:71] op_sel_hi:[1,0,1]
	v_pk_fma_f32 v[64:65], v[64:65], v[66:67], v[72:73] op_sel_hi:[1,0,1]
	v_pk_fma_f32 v[60:61], v[60:61], v[66:67], v[76:77] op_sel_hi:[1,0,1]
	v_pk_fma_f32 v[58:59], v[58:59], v[66:67], v[74:75] op_sel_hi:[1,0,1]
	v_lshl_add_u64 v[68:69], v[68:69], 0, v[210:211]
	global_store_dwordx4 v[68:69], v[62:65], off
	global_store_dwordx4 v[68:69], v[58:61], off offset:16
	v_pk_mul_f32 v[56:57], v[56:57], v[196:197]
	v_lshlrev_b32_e32 v62, 16, v156
	v_lshlrev_b32_e32 v58, 16, v154
	v_and_b32_e32 v59, 0xffff0000, v154
	v_lshlrev_b32_e32 v60, 16, v155
	v_and_b32_e32 v61, 0xffff0000, v155
	v_and_b32_e32 v63, 0xffff0000, v156
	v_pk_mul_f32 v[54:55], v[54:55], v[194:195]
	v_pk_mul_f32 v[50:51], v[50:51], v[190:191]
	v_lshlrev_b32_e32 v64, 16, v157
	v_and_b32_e32 v65, 0xffff0000, v157
	v_pk_fma_f32 v[56:57], v[56:57], v[66:67], v[60:61] op_sel_hi:[1,0,1]
	v_pk_fma_f32 v[54:55], v[54:55], v[66:67], v[58:59] op_sel_hi:[1,0,1]
	v_pk_mul_f32 v[52:53], v[52:53], v[192:193]
	v_pk_fma_f32 v[50:51], v[50:51], v[66:67], v[62:63] op_sel_hi:[1,0,1]
	v_pk_fma_f32 v[52:53], v[52:53], v[66:67], v[64:65] op_sel_hi:[1,0,1]
	global_store_dwordx4 v[68:69], v[54:57], off offset:512
	global_store_dwordx4 v[68:69], v[50:53], off offset:528
	v_lshlrev_b32_e32 v58, 16, v153
	v_lshlrev_b32_e32 v54, 16, v151
	v_add_u32_e32 v50, 0x90, v212
	v_ashrrev_i32_e32 v51, 31, v50
	v_lshlrev_b64 v[50:51], 12, v[50:51]
	v_lshlrev_b32_e32 v52, 16, v150
	v_and_b32_e32 v53, 0xffff0000, v150
	v_and_b32_e32 v55, 0xffff0000, v151
	v_lshlrev_b32_e32 v56, 16, v152
	v_and_b32_e32 v57, 0xffff0000, v152
	v_and_b32_e32 v59, 0xffff0000, v153
	v_pk_mul_f32 v[48:49], v[48:49], v[208:209]
	v_pk_mul_f32 v[46:47], v[46:47], v[206:207]
	v_mov_b32_e32 v60, v67
	v_pk_mul_f32 v[44:45], v[44:45], v[204:205]
	v_pk_mul_f32 v[42:43], v[42:43], v[202:203]
	v_lshl_add_u64 v[50:51], s[80:81], 0, v[50:51]
	v_pk_fma_f32 v[46:47], v[46:47], v[60:61], v[52:53] op_sel_hi:[1,0,1]
	v_pk_fma_f32 v[48:49], v[48:49], v[60:61], v[54:55] op_sel_hi:[1,0,1]
	v_pk_fma_f32 v[44:45], v[44:45], v[60:61], v[58:59] op_sel_hi:[1,0,1]
	v_pk_fma_f32 v[42:43], v[42:43], v[60:61], v[56:57] op_sel_hi:[1,0,1]
	v_lshl_add_u64 v[50:51], v[50:51], 0, v[210:211]
	global_store_dwordx4 v[50:51], v[46:49], off
	global_store_dwordx4 v[50:51], v[42:45], off offset:16
	v_pk_mul_f32 v[40:41], v[40:41], v[196:197]
	v_pk_mul_f32 v[38:39], v[38:39], v[194:195]
	v_lshlrev_b32_e32 v42, 16, v146
	v_and_b32_e32 v43, 0xffff0000, v146
	v_lshlrev_b32_e32 v44, 16, v147
	v_and_b32_e32 v45, 0xffff0000, v147
	v_lshlrev_b32_e32 v46, 16, v148
	v_and_b32_e32 v47, 0xffff0000, v148
	v_lshlrev_b32_e32 v48, 16, v149
	v_and_b32_e32 v49, 0xffff0000, v149
	v_pk_fma_f32 v[40:41], v[40:41], v[60:61], v[44:45] op_sel_hi:[1,0,1]
	v_pk_fma_f32 v[38:39], v[38:39], v[60:61], v[42:43] op_sel_hi:[1,0,1]
	v_pk_mul_f32 v[36:37], v[36:37], v[192:193]
	v_pk_mul_f32 v[34:35], v[34:35], v[190:191]
	v_pk_fma_f32 v[36:37], v[36:37], v[60:61], v[48:49] op_sel_hi:[1,0,1]
	v_pk_fma_f32 v[34:35], v[34:35], v[60:61], v[46:47] op_sel_hi:[1,0,1]
	global_store_dwordx4 v[50:51], v[38:41], off offset:512
	global_store_dwordx4 v[50:51], v[34:37], off offset:528
	ds_read2_b32 v[34:35], v242 offset0:160 offset1:176
	v_lshlrev_b32_e32 v38, 16, v142
	v_add_u32_e32 v36, 0xa0, v212
	v_ashrrev_i32_e32 v37, 31, v36
	v_lshlrev_b64 v[36:37], 12, v[36:37]
	v_and_b32_e32 v39, 0xffff0000, v142
	v_lshlrev_b32_e32 v40, 16, v143
	v_and_b32_e32 v41, 0xffff0000, v143
	v_lshlrev_b32_e32 v42, 16, v144
	v_and_b32_e32 v43, 0xffff0000, v144
	v_lshlrev_b32_e32 v44, 16, v145
	v_and_b32_e32 v45, 0xffff0000, v145
	v_pk_mul_f32 v[32:33], v[32:33], v[208:209]
	v_pk_mul_f32 v[30:31], v[30:31], v[206:207]
	v_pk_mul_f32 v[28:29], v[28:29], v[204:205]
	v_pk_mul_f32 v[26:27], v[26:27], v[202:203]
	v_lshl_add_u64 v[36:37], s[80:81], 0, v[36:37]
	s_waitcnt lgkmcnt(0)
	v_pk_fma_f32 v[30:31], v[30:31], v[34:35], v[38:39] op_sel_hi:[1,0,1]
	v_pk_fma_f32 v[32:33], v[32:33], v[34:35], v[40:41] op_sel_hi:[1,0,1]
	v_pk_fma_f32 v[28:29], v[28:29], v[34:35], v[44:45] op_sel_hi:[1,0,1]
	v_pk_fma_f32 v[26:27], v[26:27], v[34:35], v[42:43] op_sel_hi:[1,0,1]
	v_lshl_add_u64 v[36:37], v[36:37], 0, v[210:211]
	global_store_dwordx4 v[36:37], v[30:33], off
	global_store_dwordx4 v[36:37], v[26:29], off offset:16
	v_pk_mul_f32 v[24:25], v[24:25], v[196:197]
	v_lshlrev_b32_e32 v30, 16, v140
	v_lshlrev_b32_e32 v26, 16, v138
	v_and_b32_e32 v27, 0xffff0000, v138
	v_lshlrev_b32_e32 v28, 16, v139
	v_and_b32_e32 v29, 0xffff0000, v139
	v_and_b32_e32 v31, 0xffff0000, v140
	v_pk_mul_f32 v[22:23], v[22:23], v[194:195]
	v_pk_mul_f32 v[18:19], v[18:19], v[190:191]
	v_lshlrev_b32_e32 v32, 16, v141
	v_and_b32_e32 v33, 0xffff0000, v141
	v_pk_fma_f32 v[24:25], v[24:25], v[34:35], v[28:29] op_sel_hi:[1,0,1]
	v_pk_fma_f32 v[22:23], v[22:23], v[34:35], v[26:27] op_sel_hi:[1,0,1]
	v_pk_mul_f32 v[20:21], v[20:21], v[192:193]
	v_pk_fma_f32 v[18:19], v[18:19], v[34:35], v[30:31] op_sel_hi:[1,0,1]
	v_pk_fma_f32 v[20:21], v[20:21], v[34:35], v[32:33] op_sel_hi:[1,0,1]
	global_store_dwordx4 v[36:37], v[22:25], off offset:512
	global_store_dwordx4 v[36:37], v[18:21], off offset:528
	v_lshlrev_b32_e32 v26, 16, v137
	v_lshlrev_b32_e32 v22, 16, v135
	v_add_u32_e32 v18, 0xb0, v212
	v_ashrrev_i32_e32 v19, 31, v18
	v_lshlrev_b64 v[18:19], 12, v[18:19]
	v_lshlrev_b32_e32 v20, 16, v134
	v_and_b32_e32 v21, 0xffff0000, v134
	v_and_b32_e32 v23, 0xffff0000, v135
	v_lshlrev_b32_e32 v24, 16, v136
	v_and_b32_e32 v25, 0xffff0000, v136
	v_and_b32_e32 v27, 0xffff0000, v137
	v_pk_mul_f32 v[16:17], v[16:17], v[208:209]
	v_pk_mul_f32 v[14:15], v[14:15], v[206:207]
	v_mov_b32_e32 v28, v35
	v_pk_mul_f32 v[12:13], v[12:13], v[204:205]
	v_pk_mul_f32 v[10:11], v[10:11], v[202:203]
	v_lshl_add_u64 v[18:19], s[80:81], 0, v[18:19]
	v_pk_fma_f32 v[14:15], v[14:15], v[28:29], v[20:21] op_sel_hi:[1,0,1]
	v_pk_fma_f32 v[16:17], v[16:17], v[28:29], v[22:23] op_sel_hi:[1,0,1]
	v_pk_fma_f32 v[12:13], v[12:13], v[28:29], v[26:27] op_sel_hi:[1,0,1]
	v_pk_fma_f32 v[10:11], v[10:11], v[28:29], v[24:25] op_sel_hi:[1,0,1]
	v_lshl_add_u64 v[18:19], v[18:19], 0, v[210:211]
	global_store_dwordx4 v[18:19], v[14:17], off
	global_store_dwordx4 v[18:19], v[10:13], off offset:16
	v_pk_mul_f32 v[8:9], v[8:9], v[196:197]
	v_pk_mul_f32 v[6:7], v[6:7], v[194:195]
	v_lshlrev_b32_e32 v10, 16, v130
	v_and_b32_e32 v11, 0xffff0000, v130
	v_lshlrev_b32_e32 v12, 16, v131
	v_and_b32_e32 v13, 0xffff0000, v131
	v_lshlrev_b32_e32 v14, 16, v132
	v_and_b32_e32 v15, 0xffff0000, v132
	v_lshlrev_b32_e32 v16, 16, v133
	v_and_b32_e32 v17, 0xffff0000, v133
	v_pk_fma_f32 v[8:9], v[8:9], v[28:29], v[12:13] op_sel_hi:[1,0,1]
	v_pk_fma_f32 v[6:7], v[6:7], v[28:29], v[10:11] op_sel_hi:[1,0,1]
	v_pk_mul_f32 v[4:5], v[4:5], v[192:193]
	v_pk_mul_f32 v[2:3], v[2:3], v[190:191]
	v_pk_fma_f32 v[4:5], v[4:5], v[28:29], v[16:17] op_sel_hi:[1,0,1]
	v_pk_fma_f32 v[2:3], v[2:3], v[28:29], v[14:15] op_sel_hi:[1,0,1]
	global_store_dwordx4 v[18:19], v[6:9], off offset:512
	global_store_dwordx4 v[18:19], v[2:5], off offset:528
